# forget_bias_preload_on_clean
# speedup vs baseline: 1.0084x; 1.0084x over previous
.LBB0_235:
	s_mov_b32 s14, 0x358637bd
	v_mov_b64_e32 v[176:177], s[14:15]
	s_mov_b32 s58, 0x3a800000
	s_waitcnt lgkmcnt(0)
	v_pk_fma_f32 v[134:135], v[134:135], s[58:59], v[176:177] op_sel_hi:[1,0,0]
	v_pk_fma_f32 v[130:131], v[130:131], s[58:59], v[176:177] op_sel_hi:[1,0,0]
	v_mul_f32_e32 v0, 0x4b800000, v134
	v_cmp_gt_f32_e64 s[14:15], s77, v134
	v_cmp_gt_f32_e32 vcc, s77, v135
	s_lshl_b32 s45, s56, 8
	v_cndmask_b32_e64 v0, v134, v0, s[14:15]
	v_rsq_f32_e32 v0, v0
	s_add_i32 s45, s45, s70
	v_or_b32_e32 v192, s45, v186
	s_cmp_lt_i32 s55, 1
	v_mul_f32_e32 v134, 0x45800000, v0
	v_cndmask_b32_e64 v199, v0, v134, s[14:15]
	v_mul_f32_e32 v0, 0x4b800000, v135
	v_cndmask_b32_e32 v0, v135, v0, vcc
	v_rsq_f32_e32 v0, v0
	s_nop 0
	v_mul_f32_e32 v134, 0x45800000, v0
	v_cndmask_b32_e32 v198, v0, v134, vcc
	v_pk_fma_f32 v[134:135], v[136:137], s[58:59], v[176:177] op_sel_hi:[1,0,0]
	s_nop 0
	v_mul_f32_e32 v0, 0x4b800000, v134
	v_cmp_gt_f32_e64 s[14:15], s77, v134
	v_cmp_gt_f32_e32 vcc, s77, v135
	s_nop 0
	v_cndmask_b32_e64 v0, v134, v0, s[14:15]
	v_rsq_f32_e32 v0, v0
	s_nop 0
	v_mul_f32_e32 v134, 0x45800000, v0
	v_cndmask_b32_e64 v197, v0, v134, s[14:15]
	v_mul_f32_e32 v0, 0x4b800000, v135
	v_cndmask_b32_e32 v0, v135, v0, vcc
	v_rsq_f32_e32 v0, v0
	v_cmp_gt_f32_e64 s[14:15], s77, v130
	v_mul_f32_e32 v134, 0x45800000, v0
	v_cndmask_b32_e32 v196, v0, v134, vcc
	v_mul_f32_e32 v0, 0x4b800000, v130
	v_cndmask_b32_e64 v0, v130, v0, s[14:15]
	v_rsq_f32_e32 v0, v0
	v_cmp_gt_f32_e32 vcc, s77, v131
	v_mul_f32_e32 v130, 0x45800000, v0
	v_cndmask_b32_e64 v195, v0, v130, s[14:15]
	v_mul_f32_e32 v0, 0x4b800000, v131
	v_cndmask_b32_e32 v0, v131, v0, vcc
	v_rsq_f32_e32 v0, v0
	s_nop 0
	v_mul_f32_e32 v130, 0x45800000, v0
	v_cndmask_b32_e32 v194, v0, v130, vcc
	v_pk_fma_f32 v[130:131], v[132:133], s[58:59], v[176:177] op_sel_hi:[1,0,0]
	s_nop 0
	v_mul_f32_e32 v0, 0x4b800000, v130
	v_cmp_gt_f32_e64 s[14:15], s77, v130
	v_cmp_gt_f32_e32 vcc, s77, v131
	s_nop 0
	v_cndmask_b32_e64 v0, v130, v0, s[14:15]
	v_rsq_f32_e32 v0, v0
	s_nop 0
	v_mul_f32_e32 v130, 0x45800000, v0
	v_cndmask_b32_e64 v193, v0, v130, s[14:15]
	v_mul_f32_e32 v0, 0x4b800000, v131
	v_cndmask_b32_e32 v0, v131, v0, vcc
	v_rsq_f32_e32 v0, v0
	s_mov_b64 s[14:15], -1
	v_mul_f32_e32 v130, 0x45800000, v0
	v_cndmask_b32_e32 v191, v0, v130, vcc
	s_cbranch_scc1 .LBB0_250
	s_cmp_lg_u32 s55, 1
	s_cbranch_scc0 .LBB0_305
	s_and_saveexec_b64 s[56:57], s[36:37]
	s_cbranch_execz .LBB0_304
	global_load_dword v226, v[170:171], off
	global_load_dword v227, v[170:171], off offset:4
	global_load_dword v228, v[170:171], off offset:8
	global_load_dword v229, v[170:171], off offset:12
	s_and_saveexec_b64 s[58:59], s[4:5]
	global_load_dword v230, v[170:171], off offset:16
	s_or_b64 exec, exec, s[58:59]
	s_and_saveexec_b64 s[58:59], s[6:7]
	global_load_dword v231, v[170:171], off offset:20
	s_or_b64 exec, exec, s[58:59]
	s_and_saveexec_b64 s[58:59], s[8:9]
	global_load_dword v232, v[170:171], off offset:24
	s_or_b64 exec, exec, s[58:59]
	s_and_saveexec_b64 s[58:59], s[10:11]
	global_load_dword v233, v[170:171], off offset:28
	s_or_b64 exec, exec, s[58:59]
	s_waitcnt vmcnt(0)
	v_mov_b32_e32 v134, v226
	s_mov_b32 s55, 0xbfb8aa3b
	v_and_b32_e32 v0, 0x7fc, v192
	v_lshlrev_b32_e32 v0, 2, v0
	s_ashr_i32 s14, s45, 11
	s_mul_i32 s14, s14, 12
	s_ashr_i32 s15, s14, 31
	v_lshl_add_u64 v[132:133], s[14:15], 0, v[146:147]
	v_lshlrev_b64 v[132:133], 13, v[132:133]
	s_mov_b32 s58, 0x3f317217
	s_mov_b32 s59, 0x7f800000
	s_mov_b32 s51, 0xbfb8aa3b
	s_mov_b32 s80, 0x7f800000
	v_fmac_f32_e32 v134, v126, v199
	v_mul_f32_e64 v130, |v134|, s55
	v_exp_f32_e32 v135, v130
	v_lshl_add_u64 v[130:131], s[20:21], 0, v[0:1]
	v_lshl_add_u64 v[184:185], v[130:131], 0, v[132:133]
	v_max_f32_e64 v132, -v134, 0
	v_add_f32_e32 v0, 1.0, v135
	v_cmp_gt_f32_e32 vcc, s77, v0
	s_nop 1
	v_cndmask_b32_e64 v135, 0, 32, vcc
	v_ldexp_f32 v0, v0, v135
	v_log_f32_e32 v0, v0
	v_cndmask_b32_e32 v133, 0, v223, vcc
	v_mul_f32_e32 v134, 0x3f317217, v0
	v_fma_f32 v134, v0, s58, -v134
	v_fmac_f32_e32 v134, 0x3377d1cf, v0
	v_fmac_f32_e32 v134, 0x3f317217, v0
	v_cmp_lt_f32_e64 vcc, |v0|, s59
	s_nop 1
	v_cndmask_b32_e32 v0, v0, v134, vcc
	v_sub_f32_e32 v0, v0, v133
	v_add_f32_e32 v0, v132, v0
	v_mul_f32_e32 v0, 0xbfb8aa3b, v0
	global_store_dword v[184:185], v0, off
	v_mov_b32_e32 v0, v227
	v_fmac_f32_e32 v0, v127, v199
	v_mul_f32_e64 v132, |v0|, s55
	v_exp_f32_e32 v134, v132
	v_lshl_add_u64 v[132:133], s[14:15], 0, v[148:149]
	v_lshlrev_b64 v[132:133], 13, v[132:133]
	v_lshl_add_u64 v[182:183], v[130:131], 0, v[132:133]
	v_add_f32_e32 v134, 1.0, v134
	v_cmp_gt_f32_e32 vcc, s77, v134
	v_max_f32_e64 v0, -v0, 0
	s_nop 0
	v_cndmask_b32_e64 v135, 0, 32, vcc
	v_ldexp_f32 v134, v134, v135
	v_log_f32_e32 v134, v134
	v_cndmask_b32_e32 v132, 0, v223, vcc
	v_mul_f32_e32 v133, 0x3f317217, v134
	v_fma_f32 v133, v134, s58, -v133
	v_fmac_f32_e32 v133, 0x3377d1cf, v134
	v_fmac_f32_e32 v133, 0x3f317217, v134
	v_cmp_lt_f32_e64 vcc, |v134|, s59
	s_nop 1
	v_cndmask_b32_e32 v133, v134, v133, vcc
	v_sub_f32_e32 v132, v133, v132
	v_add_f32_e32 v0, v0, v132
	v_mul_f32_e32 v0, 0xbfb8aa3b, v0
	global_store_dword v[182:183], v0, off
	v_mov_b32_e32 v0, v228
	v_fmac_f32_e32 v0, v128, v199
	v_mul_f32_e64 v132, |v0|, s55
	v_exp_f32_e32 v134, v132
	v_lshl_add_u64 v[132:133], s[14:15], 0, v[150:151]
	v_lshlrev_b64 v[132:133], 13, v[132:133]
	v_lshl_add_u64 v[178:179], v[130:131], 0, v[132:133]
	v_add_f32_e32 v134, 1.0, v134
	v_cmp_gt_f32_e32 vcc, s77, v134
	v_max_f32_e64 v0, -v0, 0
	s_nop 0
	v_cndmask_b32_e64 v135, 0, 32, vcc
	v_ldexp_f32 v134, v134, v135
	v_log_f32_e32 v134, v134
	v_cndmask_b32_e32 v132, 0, v223, vcc
	v_mul_f32_e32 v133, 0x3f317217, v134
	v_fma_f32 v133, v134, s58, -v133
	v_fmac_f32_e32 v133, 0x3377d1cf, v134
	v_fmac_f32_e32 v133, 0x3f317217, v134
	v_cmp_lt_f32_e64 vcc, |v134|, s59
	s_nop 1
	v_cndmask_b32_e32 v133, v134, v133, vcc
	v_sub_f32_e32 v132, v133, v132
	v_add_f32_e32 v0, v0, v132
	v_mul_f32_e32 v0, 0xbfb8aa3b, v0
	global_store_dword v[178:179], v0, off
	v_mov_b32_e32 v0, v229
	v_lshl_add_u64 v[134:135], s[14:15], 0, v[154:155]
	v_fmac_f32_e32 v0, v129, v199
	v_mul_f32_e64 v132, |v0|, s55
	v_exp_f32_e32 v136, v132
	v_lshl_add_u64 v[132:133], s[14:15], 0, v[152:153]
	v_lshlrev_b64 v[132:133], 13, v[132:133]
	v_lshl_add_u64 v[180:181], v[130:131], 0, v[132:133]
	v_add_f32_e32 v136, 1.0, v136
	v_cmp_gt_f32_e32 vcc, s77, v136
	v_max_f32_e64 v0, -v0, 0
	s_mov_b32 s55, 0x3f317217
	v_cndmask_b32_e64 v137, 0, 32, vcc
	v_ldexp_f32 v136, v136, v137
	v_log_f32_e32 v136, v136
	v_cndmask_b32_e32 v132, 0, v223, vcc
	v_mul_f32_e32 v133, 0x3f317217, v136
	v_fma_f32 v133, v136, s58, -v133
	v_fmac_f32_e32 v133, 0x3377d1cf, v136
	v_fmac_f32_e32 v133, 0x3f317217, v136
	v_cmp_lt_f32_e64 vcc, |v136|, s59
	s_nop 1
	v_cndmask_b32_e32 v133, v136, v133, vcc
	v_sub_f32_e32 v132, v133, v132
	v_add_f32_e32 v0, v0, v132
	v_mul_f32_e32 v0, 0xbfb8aa3b, v0
	v_lshlrev_b64 v[132:133], 13, v[134:135]
	global_store_dword v[180:181], v0, off
	s_and_saveexec_b64 s[58:59], s[4:5]
	s_cbranch_execz .LBB0_240
	v_mov_b32_e32 v0, v230
	v_fmac_f32_e32 v0, v122, v199
	v_mul_f32_e64 v134, |v0|, s51
	v_exp_f32_e32 v134, v134
	v_max_f32_e64 v0, -v0, 0
	v_add_f32_e32 v134, 1.0, v134
	v_cmp_gt_f32_e32 vcc, s77, v134
	s_nop 1
	v_cndmask_b32_e64 v135, 0, 32, vcc
	v_ldexp_f32 v134, v134, v135
	v_log_f32_e32 v134, v134
	v_cndmask_b32_e32 v135, 0, v223, vcc
	v_mul_f32_e32 v136, 0x3f317217, v134
	v_fma_f32 v136, v134, s55, -v136
	v_fmac_f32_e32 v136, 0x3377d1cf, v134
	v_fmac_f32_e32 v136, 0x3f317217, v134
	v_cmp_lt_f32_e64 vcc, |v134|, s80
	s_nop 1
	v_cndmask_b32_e32 v134, v134, v136, vcc
	v_sub_f32_e32 v134, v134, v135
	v_add_f32_e32 v0, v0, v134
	v_mul_f32_e32 v0, 0xbfb8aa3b, v0
	v_lshl_add_u64 v[134:135], v[130:131], 0, v[132:133]
	global_store_dword v[134:135], v0, off
.LBB0_240:
	s_or_b64 exec, exec, s[58:59]
	v_lshl_add_u64 v[134:135], s[14:15], 0, v[156:157]
	v_lshlrev_b64 v[134:135], 13, v[134:135]
	s_and_saveexec_b64 s[58:59], s[6:7]
	s_cbranch_execz .LBB0_242
	v_mov_b32_e32 v0, v231
	v_fmac_f32_e32 v0, v123, v199
	v_mul_f32_e64 v136, |v0|, s51
	v_exp_f32_e32 v136, v136
	v_max_f32_e64 v0, -v0, 0
	v_add_f32_e32 v136, 1.0, v136
	v_cmp_gt_f32_e32 vcc, s77, v136
	s_nop 1
	v_cndmask_b32_e64 v137, 0, 32, vcc
	v_ldexp_f32 v136, v136, v137
	v_log_f32_e32 v136, v136
	v_cndmask_b32_e32 v137, 0, v223, vcc
	v_mul_f32_e32 v158, 0x3f317217, v136
	v_fma_f32 v158, v136, s55, -v158
	v_fmac_f32_e32 v158, 0x3377d1cf, v136
	v_fmac_f32_e32 v158, 0x3f317217, v136
	v_cmp_lt_f32_e64 vcc, |v136|, s80
	s_nop 1
	v_cndmask_b32_e32 v136, v136, v158, vcc
	v_sub_f32_e32 v136, v136, v137
	v_add_f32_e32 v0, v0, v136
	v_mul_f32_e32 v0, 0xbfb8aa3b, v0
	v_lshl_add_u64 v[136:137], v[130:131], 0, v[134:135]
	global_store_dword v[136:137], v0, off
.LBB0_242:
	s_or_b64 exec, exec, s[58:59]
	v_lshl_add_u64 v[136:137], s[14:15], 0, v[166:167]
	v_lshlrev_b64 v[136:137], 13, v[136:137]
	s_and_saveexec_b64 s[58:59], s[8:9]
	s_cbranch_execz .LBB0_244
	v_mov_b32_e32 v0, v232
	v_lshl_add_u64 v[176:177], v[130:131], 0, v[136:137]
	v_fmac_f32_e32 v0, v124, v199
	v_mul_f32_e64 v158, |v0|, s51
	v_exp_f32_e32 v158, v158
	v_max_f32_e64 v0, -v0, 0
	v_add_f32_e32 v158, 1.0, v158
	v_cmp_gt_f32_e32 vcc, s77, v158
	s_nop 1
	v_cndmask_b32_e64 v159, 0, 32, vcc
	v_ldexp_f32 v158, v158, v159
	v_log_f32_e32 v158, v158
	v_cndmask_b32_e32 v159, 0, v223, vcc
	v_mul_f32_e32 v162, 0x3f317217, v158
	v_fma_f32 v162, v158, s55, -v162
	v_fmac_f32_e32 v162, 0x3377d1cf, v158
	v_fmac_f32_e32 v162, 0x3f317217, v158
	v_cmp_lt_f32_e64 vcc, |v158|, s80
	s_nop 1
	v_cndmask_b32_e32 v158, v158, v162, vcc
	v_sub_f32_e32 v158, v158, v159
	v_add_f32_e32 v0, v0, v158
	v_mul_f32_e32 v0, 0xbfb8aa3b, v0
	global_store_dword v[176:177], v0, off
.LBB0_244:
	s_or_b64 exec, exec, s[58:59]
	v_lshl_add_u64 v[176:177], s[14:15], 0, v[168:169]
	v_lshlrev_b64 v[176:177], 13, v[176:177]
	s_and_saveexec_b64 s[14:15], s[10:11]
	s_cbranch_execz .LBB0_246
	v_mov_b32_e32 v0, v233
	v_lshl_add_u64 v[200:201], v[130:131], 0, v[176:177]
	v_fmac_f32_e32 v0, v125, v199
	v_mul_f32_e64 v158, |v0|, s51
	v_exp_f32_e32 v158, v158
	v_max_f32_e64 v0, -v0, 0
	v_add_f32_e32 v158, 1.0, v158
	v_cmp_gt_f32_e32 vcc, s77, v158
	s_nop 1
	v_cndmask_b32_e64 v159, 0, 32, vcc
	v_ldexp_f32 v158, v158, v159
	v_log_f32_e32 v158, v158
	v_cndmask_b32_e32 v159, 0, v223, vcc
	v_mul_f32_e32 v162, 0x3f317217, v158
	v_fma_f32 v162, v158, s55, -v162
	v_fmac_f32_e32 v162, 0x3377d1cf, v158
	v_fmac_f32_e32 v162, 0x3f317217, v158
	v_cmp_lt_f32_e64 vcc, |v158|, s80
	s_nop 1
	v_cndmask_b32_e32 v158, v158, v162, vcc
	v_sub_f32_e32 v158, v158, v159
	v_add_f32_e32 v0, v0, v158
	v_mul_f32_e32 v0, 0xbfb8aa3b, v0
	global_store_dword v[200:201], v0, off
.LBB0_246:
	s_or_b64 exec, exec, s[14:15]
	v_mov_b32_e32 v0, v226
	s_mov_b32 s58, 0x3f317217
	s_mov_b32 s59, 0x7f800000
	s_mov_b32 s55, 0xbfb8aa3b
	s_mov_b32 s78, 0x7f800000
	v_fmac_f32_e32 v0, v110, v198
	v_max_f32_e64 v158, -v0, 0
	v_mul_f32_e64 v0, |v0|, s51
	v_exp_f32_e32 v0, v0
	s_nop 0
	v_add_f32_e32 v0, 1.0, v0
	v_cmp_gt_f32_e32 vcc, s77, v0
	s_nop 1
	v_cndmask_b32_e64 v159, 0, 32, vcc
	v_ldexp_f32 v0, v0, v159
	v_log_f32_e32 v0, v0
	s_nop 0
	v_mul_f32_e32 v159, 0x3f317217, v0
	v_fma_f32 v159, v0, s58, -v159
	v_fmac_f32_e32 v159, 0x3377d1cf, v0
	v_fmac_f32_e32 v159, 0x3f317217, v0
	v_cmp_lt_f32_e64 s[14:15], |v0|, s59
	s_nop 1
	v_cndmask_b32_e64 v0, v0, v159, s[14:15]
	v_cndmask_b32_e32 v159, 0, v223, vcc
	v_sub_f32_e32 v0, v0, v159
	v_add_f32_e32 v0, v158, v0
	v_mul_f32_e32 v0, 0xbfb8aa3b, v0
	global_store_dword v[184:185], v0, off offset:4
	v_mov_b32_e32 v0, v227
	v_fmac_f32_e32 v0, v111, v198
	v_max_f32_e64 v158, -v0, 0
	v_mul_f32_e64 v0, |v0|, s51
	v_exp_f32_e32 v0, v0
	s_nop 0
	v_add_f32_e32 v0, 1.0, v0
	v_cmp_gt_f32_e32 vcc, s77, v0
	s_nop 1
	v_cndmask_b32_e64 v159, 0, 32, vcc
	v_ldexp_f32 v0, v0, v159
	v_log_f32_e32 v0, v0
	s_nop 0
	v_mul_f32_e32 v159, 0x3f317217, v0
	v_fma_f32 v159, v0, s58, -v159
	v_fmac_f32_e32 v159, 0x3377d1cf, v0
	v_fmac_f32_e32 v159, 0x3f317217, v0
	v_cmp_lt_f32_e64 s[14:15], |v0|, s59
	s_nop 1
	v_cndmask_b32_e64 v0, v0, v159, s[14:15]
	v_cndmask_b32_e32 v159, 0, v223, vcc
	v_sub_f32_e32 v0, v0, v159
	v_add_f32_e32 v0, v158, v0
	v_mul_f32_e32 v0, 0xbfb8aa3b, v0
	global_store_dword v[182:183], v0, off offset:4
	v_mov_b32_e32 v0, v228
	v_fmac_f32_e32 v0, v112, v198
	v_max_f32_e64 v158, -v0, 0
	v_mul_f32_e64 v0, |v0|, s51
	v_exp_f32_e32 v0, v0
	s_nop 0
	v_add_f32_e32 v0, 1.0, v0
	v_cmp_gt_f32_e32 vcc, s77, v0
	s_nop 1
	v_cndmask_b32_e64 v159, 0, 32, vcc
	v_ldexp_f32 v0, v0, v159
	v_log_f32_e32 v0, v0
	s_nop 0
	v_mul_f32_e32 v159, 0x3f317217, v0
	v_fma_f32 v159, v0, s58, -v159
	v_fmac_f32_e32 v159, 0x3377d1cf, v0
	v_fmac_f32_e32 v159, 0x3f317217, v0
	v_cmp_lt_f32_e64 s[14:15], |v0|, s59
	s_nop 1
	v_cndmask_b32_e64 v0, v0, v159, s[14:15]
	v_cndmask_b32_e32 v159, 0, v223, vcc
	v_sub_f32_e32 v0, v0, v159
	v_add_f32_e32 v0, v158, v0
	v_mul_f32_e32 v0, 0xbfb8aa3b, v0
	global_store_dword v[178:179], v0, off offset:4
	v_mov_b32_e32 v0, v229
	v_fmac_f32_e32 v0, v113, v198
	v_max_f32_e64 v158, -v0, 0
	v_mul_f32_e64 v0, |v0|, s51
	v_exp_f32_e32 v0, v0
	s_mov_b32 s51, 0x3f317217
	v_add_f32_e32 v0, 1.0, v0
	v_cmp_gt_f32_e32 vcc, s77, v0
	s_nop 1
	v_cndmask_b32_e64 v159, 0, 32, vcc
	v_ldexp_f32 v0, v0, v159
	v_log_f32_e32 v0, v0
	s_nop 0
	v_mul_f32_e32 v159, 0x3f317217, v0
	v_fma_f32 v159, v0, s58, -v159
	v_fmac_f32_e32 v159, 0x3377d1cf, v0
	v_fmac_f32_e32 v159, 0x3f317217, v0
	v_cmp_lt_f32_e64 s[14:15], |v0|, s59
	s_nop 1
	v_cndmask_b32_e64 v0, v0, v159, s[14:15]
	v_cndmask_b32_e32 v159, 0, v223, vcc
	v_sub_f32_e32 v0, v0, v159
	v_add_f32_e32 v0, v158, v0
	v_mul_f32_e32 v0, 0xbfb8aa3b, v0
	global_store_dword v[180:181], v0, off offset:4
	s_and_saveexec_b64 s[14:15], s[4:5]
	s_cbranch_execz .LBB0_252
	v_mov_b32_e32 v0, v230
	v_lshl_add_u64 v[200:201], v[130:131], 0, v[132:133]
	v_fmac_f32_e32 v0, v106, v198
	v_mul_f32_e64 v158, |v0|, s55
	v_exp_f32_e32 v158, v158
	v_max_f32_e64 v0, -v0, 0
	v_add_f32_e32 v158, 1.0, v158
	v_cmp_gt_f32_e32 vcc, s77, v158
	s_nop 1
	v_cndmask_b32_e64 v159, 0, 32, vcc
	v_ldexp_f32 v158, v158, v159
	v_log_f32_e32 v158, v158
	v_cndmask_b32_e32 v159, 0, v223, vcc
	v_mul_f32_e32 v162, 0x3f317217, v158
	v_fma_f32 v162, v158, s51, -v162
	v_fmac_f32_e32 v162, 0x3377d1cf, v158
	v_fmac_f32_e32 v162, 0x3f317217, v158
	v_cmp_lt_f32_e64 vcc, |v158|, s78
	s_nop 1
	v_cndmask_b32_e32 v158, v158, v162, vcc
	v_sub_f32_e32 v158, v158, v159
	v_add_f32_e32 v0, v0, v158
	v_mul_f32_e32 v0, 0xbfb8aa3b, v0
	global_store_dword v[200:201], v0, off offset:4
	s_or_b64 exec, exec, s[14:15]
	s_and_saveexec_b64 s[14:15], s[6:7]
	s_cbranch_execnz .LBB0_253

.LBB0_249:
	v_mov_b32_e32 v0, v232
	v_lshl_add_u64 v[200:201], v[130:131], 0, v[136:137]
	v_fmac_f32_e32 v0, v108, v198
	v_mul_f32_e64 v158, |v0|, s55
	v_exp_f32_e32 v158, v158
	v_max_f32_e64 v0, -v0, 0
	v_add_f32_e32 v158, 1.0, v158
	v_cmp_gt_f32_e32 vcc, s77, v158
	s_nop 1
	v_cndmask_b32_e64 v159, 0, 32, vcc
	v_ldexp_f32 v158, v158, v159
	v_log_f32_e32 v158, v158
	v_cndmask_b32_e32 v159, 0, v223, vcc
	v_mul_f32_e32 v162, 0x3f317217, v158
	v_fma_f32 v162, v158, s51, -v162
	v_fmac_f32_e32 v162, 0x3377d1cf, v158
	v_fmac_f32_e32 v162, 0x3f317217, v158
	v_cmp_lt_f32_e64 vcc, |v158|, s78
	s_nop 1
	v_cndmask_b32_e32 v158, v158, v162, vcc
	v_sub_f32_e32 v158, v158, v159
	v_add_f32_e32 v0, v0, v158
	v_mul_f32_e32 v0, 0xbfb8aa3b, v0
	global_store_dword v[200:201], v0, off offset:4
	s_or_b64 exec, exec, s[14:15]
	s_and_saveexec_b64 s[14:15], s[10:11]
	s_cbranch_execnz .LBB0_255
	s_branch .LBB0_256

.LBB0_253:
	v_mov_b32_e32 v0, v231
	v_lshl_add_u64 v[200:201], v[130:131], 0, v[134:135]
	v_fmac_f32_e32 v0, v107, v198
	v_mul_f32_e64 v158, |v0|, s55
	v_exp_f32_e32 v158, v158
	v_max_f32_e64 v0, -v0, 0
	v_add_f32_e32 v158, 1.0, v158
	v_cmp_gt_f32_e32 vcc, s77, v158
	s_nop 1
	v_cndmask_b32_e64 v159, 0, 32, vcc
	v_ldexp_f32 v158, v158, v159
	v_log_f32_e32 v158, v158
	v_cndmask_b32_e32 v159, 0, v223, vcc
	v_mul_f32_e32 v162, 0x3f317217, v158
	v_fma_f32 v162, v158, s51, -v162
	v_fmac_f32_e32 v162, 0x3377d1cf, v158
	v_fmac_f32_e32 v162, 0x3f317217, v158
	v_cmp_lt_f32_e64 vcc, |v158|, s78
	s_nop 1
	v_cndmask_b32_e32 v158, v158, v162, vcc
	v_sub_f32_e32 v158, v158, v159
	v_add_f32_e32 v0, v0, v158
	v_mul_f32_e32 v0, 0xbfb8aa3b, v0
	global_store_dword v[200:201], v0, off offset:4
	s_or_b64 exec, exec, s[14:15]
	s_and_saveexec_b64 s[14:15], s[8:9]
	s_cbranch_execnz .LBB0_249

.LBB0_255:
	v_mov_b32_e32 v0, v233
	v_lshl_add_u64 v[200:201], v[130:131], 0, v[176:177]
	v_fmac_f32_e32 v0, v109, v198
	v_mul_f32_e64 v158, |v0|, s55
	v_exp_f32_e32 v158, v158
	v_max_f32_e64 v0, -v0, 0
	v_add_f32_e32 v158, 1.0, v158
	v_cmp_gt_f32_e32 vcc, s77, v158
	s_nop 1
	v_cndmask_b32_e64 v159, 0, 32, vcc
	v_ldexp_f32 v158, v158, v159
	v_log_f32_e32 v158, v158
	v_cndmask_b32_e32 v159, 0, v223, vcc
	v_mul_f32_e32 v162, 0x3f317217, v158
	v_fma_f32 v162, v158, s51, -v162
	v_fmac_f32_e32 v162, 0x3377d1cf, v158
	v_fmac_f32_e32 v162, 0x3f317217, v158
	v_cmp_lt_f32_e64 vcc, |v158|, s78
	s_nop 1
	v_cndmask_b32_e32 v158, v158, v162, vcc
	v_sub_f32_e32 v158, v158, v159
	v_add_f32_e32 v0, v0, v158
	v_mul_f32_e32 v0, 0xbfb8aa3b, v0
	global_store_dword v[200:201], v0, off offset:4
.LBB0_256:
	s_or_b64 exec, exec, s[14:15]
	v_mov_b32_e32 v0, v226
	s_mov_b32 s51, 0xbfb8aa3b
	v_fmac_f32_e32 v0, v94, v197
	v_max_f32_e64 v158, -v0, 0
	v_mul_f32_e64 v0, |v0|, s51
	v_exp_f32_e32 v0, v0
	s_nop 0
	v_add_f32_e32 v0, 1.0, v0
	v_cmp_gt_f32_e32 vcc, s77, v0
	s_nop 1
	v_cndmask_b32_e64 v159, 0, 32, vcc
	v_ldexp_f32 v0, v0, v159
	v_log_f32_e32 v0, v0
	s_nop 0
	v_mul_f32_e32 v159, 0x3f317217, v0
	v_fma_f32 v159, v0, s58, -v159
	v_fmac_f32_e32 v159, 0x3377d1cf, v0
	v_fmac_f32_e32 v159, 0x3f317217, v0
	v_cmp_lt_f32_e64 s[14:15], |v0|, s59
	s_nop 1
	v_cndmask_b32_e64 v0, v0, v159, s[14:15]
	v_cndmask_b32_e32 v159, 0, v223, vcc
	v_sub_f32_e32 v0, v0, v159
	v_add_f32_e32 v0, v158, v0
	v_mul_f32_e32 v0, 0xbfb8aa3b, v0
	global_store_dword v[184:185], v0, off offset:8
	v_mov_b32_e32 v0, v227
	v_fmac_f32_e32 v0, v95, v197
	v_max_f32_e64 v158, -v0, 0
	v_mul_f32_e64 v0, |v0|, s51
	v_exp_f32_e32 v0, v0
	s_nop 0
	v_add_f32_e32 v0, 1.0, v0
	v_cmp_gt_f32_e32 vcc, s77, v0
	s_nop 1
	v_cndmask_b32_e64 v159, 0, 32, vcc
	v_ldexp_f32 v0, v0, v159
	v_log_f32_e32 v0, v0
	s_nop 0
	v_mul_f32_e32 v159, 0x3f317217, v0
	v_fma_f32 v159, v0, s58, -v159
	v_fmac_f32_e32 v159, 0x3377d1cf, v0
	v_fmac_f32_e32 v159, 0x3f317217, v0
	v_cmp_lt_f32_e64 s[14:15], |v0|, s59
	s_nop 1
	v_cndmask_b32_e64 v0, v0, v159, s[14:15]
	v_cndmask_b32_e32 v159, 0, v223, vcc
	v_sub_f32_e32 v0, v0, v159
	v_add_f32_e32 v0, v158, v0
	v_mul_f32_e32 v0, 0xbfb8aa3b, v0
	global_store_dword v[182:183], v0, off offset:8
	v_mov_b32_e32 v0, v228
	v_fmac_f32_e32 v0, v96, v197
	v_max_f32_e64 v158, -v0, 0
	v_mul_f32_e64 v0, |v0|, s51
	v_exp_f32_e32 v0, v0
	s_nop 0
	v_add_f32_e32 v0, 1.0, v0
	v_cmp_gt_f32_e32 vcc, s77, v0
	s_nop 1
	v_cndmask_b32_e64 v159, 0, 32, vcc
	v_ldexp_f32 v0, v0, v159
	v_log_f32_e32 v0, v0
	s_nop 0
	v_mul_f32_e32 v159, 0x3f317217, v0
	v_fma_f32 v159, v0, s58, -v159
	v_fmac_f32_e32 v159, 0x3377d1cf, v0
	v_fmac_f32_e32 v159, 0x3f317217, v0
	v_cmp_lt_f32_e64 s[14:15], |v0|, s59
	s_nop 1
	v_cndmask_b32_e64 v0, v0, v159, s[14:15]
	v_cndmask_b32_e32 v159, 0, v223, vcc
	v_sub_f32_e32 v0, v0, v159
	v_add_f32_e32 v0, v158, v0
	v_mul_f32_e32 v0, 0xbfb8aa3b, v0
	global_store_dword v[178:179], v0, off offset:8
	v_mov_b32_e32 v0, v229
	v_fmac_f32_e32 v0, v97, v197
	v_max_f32_e64 v158, -v0, 0
	v_mul_f32_e64 v0, |v0|, s51
	v_exp_f32_e32 v0, v0
	s_mov_b32 s51, 0x3f317217
	v_add_f32_e32 v0, 1.0, v0
	v_cmp_gt_f32_e32 vcc, s77, v0
	s_nop 1
	v_cndmask_b32_e64 v159, 0, 32, vcc
	v_ldexp_f32 v0, v0, v159
	v_log_f32_e32 v0, v0
	s_nop 0
	v_mul_f32_e32 v159, 0x3f317217, v0
	v_fma_f32 v159, v0, s58, -v159
	v_fmac_f32_e32 v159, 0x3377d1cf, v0
	v_fmac_f32_e32 v159, 0x3f317217, v0
	v_cmp_lt_f32_e64 s[14:15], |v0|, s59
	s_nop 1
	v_cndmask_b32_e64 v0, v0, v159, s[14:15]
	v_cndmask_b32_e32 v159, 0, v223, vcc
	v_sub_f32_e32 v0, v0, v159
	v_add_f32_e32 v0, v158, v0
	v_mul_f32_e32 v0, 0xbfb8aa3b, v0
	global_store_dword v[180:181], v0, off offset:8
	s_and_saveexec_b64 s[14:15], s[4:5]
	s_cbranch_execz .LBB0_260
	v_mov_b32_e32 v0, v230
	v_lshl_add_u64 v[200:201], v[130:131], 0, v[132:133]
	v_fmac_f32_e32 v0, v90, v197
	v_mul_f32_e64 v158, |v0|, s55
	v_exp_f32_e32 v158, v158
	v_max_f32_e64 v0, -v0, 0
	v_add_f32_e32 v158, 1.0, v158
	v_cmp_gt_f32_e32 vcc, s77, v158
	s_nop 1
	v_cndmask_b32_e64 v159, 0, 32, vcc
	v_ldexp_f32 v158, v158, v159
	v_log_f32_e32 v158, v158
	v_cndmask_b32_e32 v159, 0, v223, vcc
	v_mul_f32_e32 v162, 0x3f317217, v158
	v_fma_f32 v162, v158, s51, -v162
	v_fmac_f32_e32 v162, 0x3377d1cf, v158
	v_fmac_f32_e32 v162, 0x3f317217, v158
	v_cmp_lt_f32_e64 vcc, |v158|, s78
	s_nop 1
	v_cndmask_b32_e32 v158, v158, v162, vcc
	v_sub_f32_e32 v158, v158, v159
	v_add_f32_e32 v0, v0, v158
	v_mul_f32_e32 v0, 0xbfb8aa3b, v0
	global_store_dword v[200:201], v0, off offset:8
	s_or_b64 exec, exec, s[14:15]
	s_and_saveexec_b64 s[14:15], s[6:7]
	s_cbranch_execnz .LBB0_261

.LBB0_259:
	v_mov_b32_e32 v0, v232
	v_lshl_add_u64 v[200:201], v[130:131], 0, v[136:137]
	v_fmac_f32_e32 v0, v92, v197
	v_mul_f32_e64 v158, |v0|, s55
	v_exp_f32_e32 v158, v158
	v_max_f32_e64 v0, -v0, 0
	v_add_f32_e32 v158, 1.0, v158
	v_cmp_gt_f32_e32 vcc, s77, v158
	s_nop 1
	v_cndmask_b32_e64 v159, 0, 32, vcc
	v_ldexp_f32 v158, v158, v159
	v_log_f32_e32 v158, v158
	v_cndmask_b32_e32 v159, 0, v223, vcc
	v_mul_f32_e32 v162, 0x3f317217, v158
	v_fma_f32 v162, v158, s51, -v162
	v_fmac_f32_e32 v162, 0x3377d1cf, v158
	v_fmac_f32_e32 v162, 0x3f317217, v158
	v_cmp_lt_f32_e64 vcc, |v158|, s78
	s_nop 1
	v_cndmask_b32_e32 v158, v158, v162, vcc
	v_sub_f32_e32 v158, v158, v159
	v_add_f32_e32 v0, v0, v158
	v_mul_f32_e32 v0, 0xbfb8aa3b, v0
	global_store_dword v[200:201], v0, off offset:8
	s_or_b64 exec, exec, s[14:15]
	s_and_saveexec_b64 s[14:15], s[10:11]
	s_cbranch_execnz .LBB0_263
	s_branch .LBB0_264

.LBB0_261:
	v_mov_b32_e32 v0, v231
	v_lshl_add_u64 v[200:201], v[130:131], 0, v[134:135]
	v_fmac_f32_e32 v0, v91, v197
	v_mul_f32_e64 v158, |v0|, s55
	v_exp_f32_e32 v158, v158
	v_max_f32_e64 v0, -v0, 0
	v_add_f32_e32 v158, 1.0, v158
	v_cmp_gt_f32_e32 vcc, s77, v158
	s_nop 1
	v_cndmask_b32_e64 v159, 0, 32, vcc
	v_ldexp_f32 v158, v158, v159
	v_log_f32_e32 v158, v158
	v_cndmask_b32_e32 v159, 0, v223, vcc
	v_mul_f32_e32 v162, 0x3f317217, v158
	v_fma_f32 v162, v158, s51, -v162
	v_fmac_f32_e32 v162, 0x3377d1cf, v158
	v_fmac_f32_e32 v162, 0x3f317217, v158
	v_cmp_lt_f32_e64 vcc, |v158|, s78
	s_nop 1
	v_cndmask_b32_e32 v158, v158, v162, vcc
	v_sub_f32_e32 v158, v158, v159
	v_add_f32_e32 v0, v0, v158
	v_mul_f32_e32 v0, 0xbfb8aa3b, v0
	global_store_dword v[200:201], v0, off offset:8
	s_or_b64 exec, exec, s[14:15]
	s_and_saveexec_b64 s[14:15], s[8:9]
	s_cbranch_execnz .LBB0_259

.LBB0_263:
	v_mov_b32_e32 v0, v233
	v_lshl_add_u64 v[200:201], v[130:131], 0, v[176:177]
	v_fmac_f32_e32 v0, v93, v197
	v_mul_f32_e64 v158, |v0|, s55
	v_exp_f32_e32 v158, v158
	v_max_f32_e64 v0, -v0, 0
	v_add_f32_e32 v158, 1.0, v158
	v_cmp_gt_f32_e32 vcc, s77, v158
	s_nop 1
	v_cndmask_b32_e64 v159, 0, 32, vcc
	v_ldexp_f32 v158, v158, v159
	v_log_f32_e32 v158, v158
	v_cndmask_b32_e32 v159, 0, v223, vcc
	v_mul_f32_e32 v162, 0x3f317217, v158
	v_fma_f32 v162, v158, s51, -v162
	v_fmac_f32_e32 v162, 0x3377d1cf, v158
	v_fmac_f32_e32 v162, 0x3f317217, v158
	v_cmp_lt_f32_e64 vcc, |v158|, s78
	s_nop 1
	v_cndmask_b32_e32 v158, v158, v162, vcc
	v_sub_f32_e32 v158, v158, v159
	v_add_f32_e32 v0, v0, v158
	v_mul_f32_e32 v0, 0xbfb8aa3b, v0
	global_store_dword v[200:201], v0, off offset:8
.LBB0_264:
	s_or_b64 exec, exec, s[14:15]
	v_mov_b32_e32 v0, v226
	s_mov_b32 s51, 0xbfb8aa3b
	v_fmac_f32_e32 v0, v78, v196
	v_max_f32_e64 v158, -v0, 0
	v_mul_f32_e64 v0, |v0|, s51
	v_exp_f32_e32 v0, v0
	s_nop 0
	v_add_f32_e32 v0, 1.0, v0
	v_cmp_gt_f32_e32 vcc, s77, v0
	s_nop 1
	v_cndmask_b32_e64 v159, 0, 32, vcc
	v_ldexp_f32 v0, v0, v159
	v_log_f32_e32 v0, v0
	s_nop 0
	v_mul_f32_e32 v159, 0x3f317217, v0
	v_fma_f32 v159, v0, s58, -v159
	v_fmac_f32_e32 v159, 0x3377d1cf, v0
	v_fmac_f32_e32 v159, 0x3f317217, v0
	v_cmp_lt_f32_e64 s[14:15], |v0|, s59
	s_nop 1
	v_cndmask_b32_e64 v0, v0, v159, s[14:15]
	v_cndmask_b32_e32 v159, 0, v223, vcc
	v_sub_f32_e32 v0, v0, v159
	v_add_f32_e32 v0, v158, v0
	v_mul_f32_e32 v0, 0xbfb8aa3b, v0
	global_store_dword v[184:185], v0, off offset:12
	v_mov_b32_e32 v0, v227
	v_fmac_f32_e32 v0, v79, v196
	v_max_f32_e64 v158, -v0, 0
	v_mul_f32_e64 v0, |v0|, s51
	v_exp_f32_e32 v0, v0
	s_nop 0
	v_add_f32_e32 v0, 1.0, v0
	v_cmp_gt_f32_e32 vcc, s77, v0
	s_nop 1
	v_cndmask_b32_e64 v159, 0, 32, vcc
	v_ldexp_f32 v0, v0, v159
	v_log_f32_e32 v0, v0
	s_nop 0
	v_mul_f32_e32 v159, 0x3f317217, v0
	v_fma_f32 v159, v0, s58, -v159
	v_fmac_f32_e32 v159, 0x3377d1cf, v0
	v_fmac_f32_e32 v159, 0x3f317217, v0
	v_cmp_lt_f32_e64 s[14:15], |v0|, s59
	s_nop 1
	v_cndmask_b32_e64 v0, v0, v159, s[14:15]
	v_cndmask_b32_e32 v159, 0, v223, vcc
	v_sub_f32_e32 v0, v0, v159
	v_add_f32_e32 v0, v158, v0
	v_mul_f32_e32 v0, 0xbfb8aa3b, v0
	global_store_dword v[182:183], v0, off offset:12
	v_mov_b32_e32 v0, v228
	v_fmac_f32_e32 v0, v80, v196
	v_max_f32_e64 v158, -v0, 0
	v_mul_f32_e64 v0, |v0|, s51
	v_exp_f32_e32 v0, v0
	s_nop 0
	v_add_f32_e32 v0, 1.0, v0
	v_cmp_gt_f32_e32 vcc, s77, v0
	s_nop 1
	v_cndmask_b32_e64 v159, 0, 32, vcc
	v_ldexp_f32 v0, v0, v159
	v_log_f32_e32 v0, v0
	s_nop 0
	v_mul_f32_e32 v159, 0x3f317217, v0
	v_fma_f32 v159, v0, s58, -v159
	v_fmac_f32_e32 v159, 0x3377d1cf, v0
	v_fmac_f32_e32 v159, 0x3f317217, v0
	v_cmp_lt_f32_e64 s[14:15], |v0|, s59
	s_nop 1
	v_cndmask_b32_e64 v0, v0, v159, s[14:15]
	v_cndmask_b32_e32 v159, 0, v223, vcc
	v_sub_f32_e32 v0, v0, v159
	v_add_f32_e32 v0, v158, v0
	v_mul_f32_e32 v0, 0xbfb8aa3b, v0
	global_store_dword v[178:179], v0, off offset:12
	v_mov_b32_e32 v0, v229
	v_fmac_f32_e32 v0, v81, v196
	v_max_f32_e64 v158, -v0, 0
	v_mul_f32_e64 v0, |v0|, s51
	v_exp_f32_e32 v0, v0
	s_mov_b32 s51, 0x3f317217
	v_add_f32_e32 v0, 1.0, v0
	v_cmp_gt_f32_e32 vcc, s77, v0
	s_nop 1
	v_cndmask_b32_e64 v159, 0, 32, vcc
	v_ldexp_f32 v0, v0, v159
	v_log_f32_e32 v0, v0
	s_nop 0
	v_mul_f32_e32 v159, 0x3f317217, v0
	v_fma_f32 v159, v0, s58, -v159
	v_fmac_f32_e32 v159, 0x3377d1cf, v0
	v_fmac_f32_e32 v159, 0x3f317217, v0
	v_cmp_lt_f32_e64 s[14:15], |v0|, s59
	s_nop 1
	v_cndmask_b32_e64 v0, v0, v159, s[14:15]
	v_cndmask_b32_e32 v159, 0, v223, vcc
	v_sub_f32_e32 v0, v0, v159
	v_add_f32_e32 v0, v158, v0
	v_mul_f32_e32 v0, 0xbfb8aa3b, v0
	global_store_dword v[180:181], v0, off offset:12
	s_and_saveexec_b64 s[14:15], s[4:5]
	s_cbranch_execz .LBB0_268
	v_mov_b32_e32 v0, v230
	v_lshl_add_u64 v[132:133], v[130:131], 0, v[132:133]
	v_fmac_f32_e32 v0, v74, v196
	v_mul_f32_e64 v158, |v0|, s55
	v_exp_f32_e32 v158, v158
	v_max_f32_e64 v0, -v0, 0
	v_add_f32_e32 v158, 1.0, v158
	v_cmp_gt_f32_e32 vcc, s77, v158
	s_nop 1
	v_cndmask_b32_e64 v159, 0, 32, vcc
	v_ldexp_f32 v158, v158, v159
	v_log_f32_e32 v158, v158
	v_cndmask_b32_e32 v159, 0, v223, vcc
	v_mul_f32_e32 v162, 0x3f317217, v158
	v_fma_f32 v162, v158, s51, -v162
	v_fmac_f32_e32 v162, 0x3377d1cf, v158
	v_fmac_f32_e32 v162, 0x3f317217, v158
	v_cmp_lt_f32_e64 vcc, |v158|, s78
	s_nop 1
	v_cndmask_b32_e32 v158, v158, v162, vcc
	v_sub_f32_e32 v158, v158, v159
	v_add_f32_e32 v0, v0, v158
	v_mul_f32_e32 v0, 0xbfb8aa3b, v0
	global_store_dword v[132:133], v0, off offset:12
	s_or_b64 exec, exec, s[14:15]
	s_and_saveexec_b64 s[14:15], s[6:7]
	s_cbranch_execnz .LBB0_269

.LBB0_267:
	v_mov_b32_e32 v0, v232
	v_fmac_f32_e32 v0, v76, v196
	v_mul_f32_e64 v132, |v0|, s55
	v_exp_f32_e32 v132, v132
	v_max_f32_e64 v0, -v0, 0
	v_add_f32_e32 v132, 1.0, v132
	v_cmp_gt_f32_e32 vcc, s77, v132
	s_nop 1
	v_cndmask_b32_e64 v133, 0, 32, vcc
	v_ldexp_f32 v132, v132, v133
	v_log_f32_e32 v132, v132
	v_cndmask_b32_e32 v133, 0, v223, vcc
	v_mul_f32_e32 v134, 0x3f317217, v132
	v_fma_f32 v134, v132, s51, -v134
	v_fmac_f32_e32 v134, 0x3377d1cf, v132
	v_fmac_f32_e32 v134, 0x3f317217, v132
	v_cmp_lt_f32_e64 vcc, |v132|, s78
	s_nop 1
	v_cndmask_b32_e32 v132, v132, v134, vcc
	v_sub_f32_e32 v132, v132, v133
	v_add_f32_e32 v0, v0, v132
	v_mul_f32_e32 v0, 0xbfb8aa3b, v0
	v_lshl_add_u64 v[132:133], v[130:131], 0, v[136:137]
	global_store_dword v[132:133], v0, off offset:12
	s_or_b64 exec, exec, s[14:15]
	s_and_saveexec_b64 s[14:15], s[10:11]
	s_cbranch_execnz .LBB0_271
	s_branch .LBB0_272

.LBB0_269:
	v_mov_b32_e32 v0, v231
	v_fmac_f32_e32 v0, v75, v196
	v_mul_f32_e64 v132, |v0|, s55
	v_exp_f32_e32 v132, v132
	v_max_f32_e64 v0, -v0, 0
	v_add_f32_e32 v132, 1.0, v132
	v_cmp_gt_f32_e32 vcc, s77, v132
	s_nop 1
	v_cndmask_b32_e64 v133, 0, 32, vcc
	v_ldexp_f32 v132, v132, v133
	v_log_f32_e32 v132, v132
	v_cndmask_b32_e32 v133, 0, v223, vcc
	v_mul_f32_e32 v158, 0x3f317217, v132
	v_fma_f32 v158, v132, s51, -v158
	v_fmac_f32_e32 v158, 0x3377d1cf, v132
	v_fmac_f32_e32 v158, 0x3f317217, v132
	v_cmp_lt_f32_e64 vcc, |v132|, s78
	s_nop 1
	v_cndmask_b32_e32 v132, v132, v158, vcc
	v_sub_f32_e32 v132, v132, v133
	v_add_f32_e32 v0, v0, v132
	v_mul_f32_e32 v0, 0xbfb8aa3b, v0
	v_lshl_add_u64 v[132:133], v[130:131], 0, v[134:135]
	global_store_dword v[132:133], v0, off offset:12
	s_or_b64 exec, exec, s[14:15]
	s_and_saveexec_b64 s[14:15], s[8:9]
	s_cbranch_execnz .LBB0_267

.LBB0_271:
	v_mov_b32_e32 v0, v233
	v_lshl_add_u64 v[130:131], v[130:131], 0, v[176:177]
	v_fmac_f32_e32 v0, v77, v196
	v_mul_f32_e64 v132, |v0|, s55
	v_exp_f32_e32 v132, v132
	v_max_f32_e64 v0, -v0, 0
	v_add_f32_e32 v132, 1.0, v132
	v_cmp_gt_f32_e32 vcc, s77, v132
	s_nop 1
	v_cndmask_b32_e64 v133, 0, 32, vcc
	v_ldexp_f32 v132, v132, v133
	v_log_f32_e32 v132, v132
	v_cndmask_b32_e32 v133, 0, v223, vcc
	v_mul_f32_e32 v134, 0x3f317217, v132
	v_fma_f32 v134, v132, s51, -v134
	v_fmac_f32_e32 v134, 0x3377d1cf, v132
	v_fmac_f32_e32 v134, 0x3f317217, v132
	v_cmp_lt_f32_e64 vcc, |v132|, s78
	s_nop 1
	v_cndmask_b32_e32 v132, v132, v134, vcc
	v_sub_f32_e32 v132, v132, v133
	v_add_f32_e32 v0, v0, v132
	v_mul_f32_e32 v0, 0xbfb8aa3b, v0
	global_store_dword v[130:131], v0, off offset:12
.LBB0_272:
	s_or_b64 exec, exec, s[14:15]
	v_mov_b32_e32 v134, v226
	v_add_u32_e32 v0, 0x80, v192
	v_ashrrev_i32_e32 v130, 11, v0
	s_mov_b32 s14, 0xbfb8aa3b
	v_mul_i32_i24_e32 v176, 12, v130
	v_and_b32_e32 v0, 0x7fc, v0
	v_lshlrev_b32_e32 v0, 2, v0
	v_ashrrev_i32_e32 v177, 31, v176
	v_lshl_add_u64 v[132:133], v[176:177], 0, v[146:147]
	v_lshlrev_b64 v[132:133], 13, v[132:133]
	s_mov_b32 s15, 0x3f317217
	s_mov_b32 s58, 0x7f800000
	s_mov_b32 s51, 0xbfb8aa3b
	s_mov_b32 s55, 0x3f317217
	v_fmac_f32_e32 v134, v62, v195
	v_mul_f32_e64 v130, |v134|, s14
	v_exp_f32_e32 v135, v130
	v_lshl_add_u64 v[130:131], s[20:21], 0, v[0:1]
	v_lshl_add_u64 v[184:185], v[130:131], 0, v[132:133]
	v_max_f32_e64 v132, -v134, 0
	v_add_f32_e32 v0, 1.0, v135
	v_cmp_gt_f32_e32 vcc, s77, v0
	s_nop 1
	v_cndmask_b32_e64 v135, 0, 32, vcc
	v_ldexp_f32 v0, v0, v135
	v_log_f32_e32 v0, v0
	v_cndmask_b32_e32 v133, 0, v223, vcc
	v_mul_f32_e32 v134, 0x3f317217, v0
	v_fma_f32 v134, v0, s15, -v134
	v_fmac_f32_e32 v134, 0x3377d1cf, v0
	v_fmac_f32_e32 v134, 0x3f317217, v0
	v_cmp_lt_f32_e64 vcc, |v0|, s58
	s_nop 1
	v_cndmask_b32_e32 v0, v0, v134, vcc
	v_sub_f32_e32 v0, v0, v133
	v_add_f32_e32 v0, v132, v0
	v_mul_f32_e32 v0, 0xbfb8aa3b, v0
	global_store_dword v[184:185], v0, off
	v_mov_b32_e32 v0, v227
	v_fmac_f32_e32 v0, v63, v195
	v_mul_f32_e64 v132, |v0|, s14
	v_exp_f32_e32 v134, v132
	v_lshl_add_u64 v[132:133], v[176:177], 0, v[148:149]
	v_lshlrev_b64 v[132:133], 13, v[132:133]
	v_lshl_add_u64 v[182:183], v[130:131], 0, v[132:133]
	v_add_f32_e32 v134, 1.0, v134
	v_cmp_gt_f32_e32 vcc, s77, v134
	v_max_f32_e64 v0, -v0, 0
	s_nop 0
	v_cndmask_b32_e64 v135, 0, 32, vcc
	v_ldexp_f32 v134, v134, v135
	v_log_f32_e32 v134, v134
	v_cndmask_b32_e32 v132, 0, v223, vcc
	v_mul_f32_e32 v133, 0x3f317217, v134
	v_fma_f32 v133, v134, s15, -v133
	v_fmac_f32_e32 v133, 0x3377d1cf, v134
	v_fmac_f32_e32 v133, 0x3f317217, v134
	v_cmp_lt_f32_e64 vcc, |v134|, s58
	s_nop 1
	v_cndmask_b32_e32 v133, v134, v133, vcc
	v_sub_f32_e32 v132, v133, v132
	v_add_f32_e32 v0, v0, v132
	v_mul_f32_e32 v0, 0xbfb8aa3b, v0
	global_store_dword v[182:183], v0, off
	v_mov_b32_e32 v0, v228
	v_fmac_f32_e32 v0, v64, v195
	v_mul_f32_e64 v132, |v0|, s14
	v_exp_f32_e32 v134, v132
	v_lshl_add_u64 v[132:133], v[176:177], 0, v[150:151]
	v_lshlrev_b64 v[132:133], 13, v[132:133]
	v_lshl_add_u64 v[178:179], v[130:131], 0, v[132:133]
	v_add_f32_e32 v134, 1.0, v134
	v_cmp_gt_f32_e32 vcc, s77, v134
	v_max_f32_e64 v0, -v0, 0
	s_nop 0
	v_cndmask_b32_e64 v135, 0, 32, vcc
	v_ldexp_f32 v134, v134, v135
	v_log_f32_e32 v134, v134
	v_cndmask_b32_e32 v132, 0, v223, vcc
	v_mul_f32_e32 v133, 0x3f317217, v134
	v_fma_f32 v133, v134, s15, -v133
	v_fmac_f32_e32 v133, 0x3377d1cf, v134
	v_fmac_f32_e32 v133, 0x3f317217, v134
	v_cmp_lt_f32_e64 vcc, |v134|, s58
	s_nop 1
	v_cndmask_b32_e32 v133, v134, v133, vcc
	v_sub_f32_e32 v132, v133, v132
	v_add_f32_e32 v0, v0, v132
	v_mul_f32_e32 v0, 0xbfb8aa3b, v0
	global_store_dword v[178:179], v0, off
	v_mov_b32_e32 v0, v229
	v_lshl_add_u64 v[134:135], v[176:177], 0, v[154:155]
	v_fmac_f32_e32 v0, v65, v195
	v_mul_f32_e64 v132, |v0|, s14
	v_exp_f32_e32 v136, v132
	v_lshl_add_u64 v[132:133], v[176:177], 0, v[152:153]
	v_lshlrev_b64 v[132:133], 13, v[132:133]
	v_lshl_add_u64 v[180:181], v[130:131], 0, v[132:133]
	v_add_f32_e32 v136, 1.0, v136
	v_cmp_gt_f32_e32 vcc, s77, v136
	v_max_f32_e64 v0, -v0, 0
	s_nop 0
	v_cndmask_b32_e64 v137, 0, 32, vcc
	v_ldexp_f32 v136, v136, v137
	v_log_f32_e32 v136, v136
	v_cndmask_b32_e32 v132, 0, v223, vcc
	v_mul_f32_e32 v133, 0x3f317217, v136
	v_fma_f32 v133, v136, s15, -v133
	v_fmac_f32_e32 v133, 0x3377d1cf, v136
	v_fmac_f32_e32 v133, 0x3f317217, v136
	v_cmp_lt_f32_e64 vcc, |v136|, s58
	s_nop 1
	v_cndmask_b32_e32 v133, v136, v133, vcc
	v_sub_f32_e32 v132, v133, v132
	v_add_f32_e32 v0, v0, v132
	v_mul_f32_e32 v0, 0xbfb8aa3b, v0
	v_lshlrev_b64 v[132:133], 13, v[134:135]
	global_store_dword v[180:181], v0, off
	s_and_saveexec_b64 s[14:15], s[4:5]
	s_cbranch_execz .LBB0_274
	v_mov_b32_e32 v0, v230
	v_fmac_f32_e32 v0, v58, v195
	v_mul_f32_e64 v134, |v0|, s51
	v_exp_f32_e32 v134, v134
	v_max_f32_e64 v0, -v0, 0
	v_add_f32_e32 v134, 1.0, v134
	v_cmp_gt_f32_e32 vcc, s77, v134
	s_nop 1
	v_cndmask_b32_e64 v135, 0, 32, vcc
	v_ldexp_f32 v134, v134, v135
	v_log_f32_e32 v134, v134
	v_cndmask_b32_e32 v135, 0, v223, vcc
	v_mul_f32_e32 v136, 0x3f317217, v134
	v_fma_f32 v136, v134, s55, -v136
	v_fmac_f32_e32 v136, 0x3377d1cf, v134
	v_fmac_f32_e32 v136, 0x3f317217, v134
	v_cmp_lt_f32_e64 vcc, |v134|, s78
	s_nop 1
	v_cndmask_b32_e32 v134, v134, v136, vcc
	v_sub_f32_e32 v134, v134, v135
	v_add_f32_e32 v0, v0, v134
	v_mul_f32_e32 v0, 0xbfb8aa3b, v0
	v_lshl_add_u64 v[134:135], v[130:131], 0, v[132:133]
	global_store_dword v[134:135], v0, off
.LBB0_274:
	s_or_b64 exec, exec, s[14:15]
	v_lshl_add_u64 v[134:135], v[176:177], 0, v[156:157]
	v_lshlrev_b64 v[134:135], 13, v[134:135]
	s_and_saveexec_b64 s[14:15], s[6:7]
	s_cbranch_execz .LBB0_276
	v_mov_b32_e32 v0, v231
	v_fmac_f32_e32 v0, v59, v195
	v_mul_f32_e64 v136, |v0|, s51
	v_exp_f32_e32 v136, v136
	v_max_f32_e64 v0, -v0, 0
	v_add_f32_e32 v136, 1.0, v136
	v_cmp_gt_f32_e32 vcc, s77, v136
	s_nop 1
	v_cndmask_b32_e64 v137, 0, 32, vcc
	v_ldexp_f32 v136, v136, v137
	v_log_f32_e32 v136, v136
	v_cndmask_b32_e32 v137, 0, v223, vcc
	v_mul_f32_e32 v158, 0x3f317217, v136
	v_fma_f32 v158, v136, s55, -v158
	v_fmac_f32_e32 v158, 0x3377d1cf, v136
	v_fmac_f32_e32 v158, 0x3f317217, v136
	v_cmp_lt_f32_e64 vcc, |v136|, s78
	s_nop 1
	v_cndmask_b32_e32 v136, v136, v158, vcc
	v_sub_f32_e32 v136, v136, v137
	v_add_f32_e32 v0, v0, v136
	v_mul_f32_e32 v0, 0xbfb8aa3b, v0
	v_lshl_add_u64 v[136:137], v[130:131], 0, v[134:135]
	global_store_dword v[136:137], v0, off
.LBB0_276:
	s_or_b64 exec, exec, s[14:15]
	v_lshl_add_u64 v[136:137], v[176:177], 0, v[166:167]
	v_lshlrev_b64 v[136:137], 13, v[136:137]
	s_and_saveexec_b64 s[14:15], s[8:9]
	s_cbranch_execz .LBB0_278
	v_mov_b32_e32 v0, v232
	v_lshl_add_u64 v[200:201], v[130:131], 0, v[136:137]
	v_fmac_f32_e32 v0, v60, v195
	v_mul_f32_e64 v158, |v0|, s51
	v_exp_f32_e32 v158, v158
	v_max_f32_e64 v0, -v0, 0
	v_add_f32_e32 v158, 1.0, v158
	v_cmp_gt_f32_e32 vcc, s77, v158
	s_nop 1
	v_cndmask_b32_e64 v159, 0, 32, vcc
	v_ldexp_f32 v158, v158, v159
	v_log_f32_e32 v158, v158
	v_cndmask_b32_e32 v159, 0, v223, vcc
	v_mul_f32_e32 v162, 0x3f317217, v158
	v_fma_f32 v162, v158, s55, -v162
	v_fmac_f32_e32 v162, 0x3377d1cf, v158
	v_fmac_f32_e32 v162, 0x3f317217, v158
	v_cmp_lt_f32_e64 vcc, |v158|, s78
	s_nop 1
	v_cndmask_b32_e32 v158, v158, v162, vcc
	v_sub_f32_e32 v158, v158, v159
	v_add_f32_e32 v0, v0, v158
	v_mul_f32_e32 v0, 0xbfb8aa3b, v0
	global_store_dword v[200:201], v0, off
.LBB0_278:
	s_or_b64 exec, exec, s[14:15]
	v_lshl_add_u64 v[176:177], v[176:177], 0, v[168:169]
	v_lshlrev_b64 v[176:177], 13, v[176:177]
	s_and_saveexec_b64 s[14:15], s[10:11]
	s_cbranch_execz .LBB0_280
	v_mov_b32_e32 v0, v233
	v_lshl_add_u64 v[200:201], v[130:131], 0, v[176:177]
	v_fmac_f32_e32 v0, v61, v195
	v_mul_f32_e64 v158, |v0|, s51
	v_exp_f32_e32 v158, v158
	v_max_f32_e64 v0, -v0, 0
	v_add_f32_e32 v158, 1.0, v158
	v_cmp_gt_f32_e32 vcc, s77, v158
	s_nop 1
	v_cndmask_b32_e64 v159, 0, 32, vcc
	v_ldexp_f32 v158, v158, v159
	v_log_f32_e32 v158, v158
	v_cndmask_b32_e32 v159, 0, v223, vcc
	v_mul_f32_e32 v162, 0x3f317217, v158
	v_fma_f32 v162, v158, s55, -v162
	v_fmac_f32_e32 v162, 0x3377d1cf, v158
	v_fmac_f32_e32 v162, 0x3f317217, v158
	v_cmp_lt_f32_e64 vcc, |v158|, s78
	s_nop 1
	v_cndmask_b32_e32 v158, v158, v162, vcc
	v_sub_f32_e32 v158, v158, v159
	v_add_f32_e32 v0, v0, v158
	v_mul_f32_e32 v0, 0xbfb8aa3b, v0
	global_store_dword v[200:201], v0, off
.LBB0_280:
	s_or_b64 exec, exec, s[14:15]
	v_mov_b32_e32 v0, v226
	s_mov_b32 s58, 0x3f317217
	s_mov_b32 s55, 0xbfb8aa3b
	v_fmac_f32_e32 v0, v46, v194
	v_max_f32_e64 v158, -v0, 0
	v_mul_f32_e64 v0, |v0|, s51
	v_exp_f32_e32 v0, v0
	s_nop 0
	v_add_f32_e32 v0, 1.0, v0
	v_cmp_gt_f32_e32 vcc, s77, v0
	s_nop 1
	v_cndmask_b32_e64 v159, 0, 32, vcc
	v_ldexp_f32 v0, v0, v159
	v_log_f32_e32 v0, v0
	s_nop 0
	v_mul_f32_e32 v159, 0x3f317217, v0
	v_fma_f32 v159, v0, s58, -v159
	v_fmac_f32_e32 v159, 0x3377d1cf, v0
	v_fmac_f32_e32 v159, 0x3f317217, v0
	v_cmp_lt_f32_e64 s[14:15], |v0|, s59
	s_nop 1
	v_cndmask_b32_e64 v0, v0, v159, s[14:15]
	v_cndmask_b32_e32 v159, 0, v223, vcc
	v_sub_f32_e32 v0, v0, v159
	v_add_f32_e32 v0, v158, v0
	v_mul_f32_e32 v0, 0xbfb8aa3b, v0
	global_store_dword v[184:185], v0, off offset:4
	v_mov_b32_e32 v0, v227
	v_fmac_f32_e32 v0, v47, v194
	v_max_f32_e64 v158, -v0, 0
	v_mul_f32_e64 v0, |v0|, s51
	v_exp_f32_e32 v0, v0
	s_nop 0
	v_add_f32_e32 v0, 1.0, v0
	v_cmp_gt_f32_e32 vcc, s77, v0
	s_nop 1
	v_cndmask_b32_e64 v159, 0, 32, vcc
	v_ldexp_f32 v0, v0, v159
	v_log_f32_e32 v0, v0
	s_nop 0
	v_mul_f32_e32 v159, 0x3f317217, v0
	v_fma_f32 v159, v0, s58, -v159
	v_fmac_f32_e32 v159, 0x3377d1cf, v0
	v_fmac_f32_e32 v159, 0x3f317217, v0
	v_cmp_lt_f32_e64 s[14:15], |v0|, s59
	s_nop 1
	v_cndmask_b32_e64 v0, v0, v159, s[14:15]
	v_cndmask_b32_e32 v159, 0, v223, vcc
	v_sub_f32_e32 v0, v0, v159
	v_add_f32_e32 v0, v158, v0
	v_mul_f32_e32 v0, 0xbfb8aa3b, v0
	global_store_dword v[182:183], v0, off offset:4
	v_mov_b32_e32 v0, v228
	v_fmac_f32_e32 v0, v48, v194
	v_max_f32_e64 v158, -v0, 0
	v_mul_f32_e64 v0, |v0|, s51
	v_exp_f32_e32 v0, v0
	s_nop 0
	v_add_f32_e32 v0, 1.0, v0
	v_cmp_gt_f32_e32 vcc, s77, v0
	s_nop 1
	v_cndmask_b32_e64 v159, 0, 32, vcc
	v_ldexp_f32 v0, v0, v159
	v_log_f32_e32 v0, v0
	s_nop 0
	v_mul_f32_e32 v159, 0x3f317217, v0
	v_fma_f32 v159, v0, s58, -v159
	v_fmac_f32_e32 v159, 0x3377d1cf, v0
	v_fmac_f32_e32 v159, 0x3f317217, v0
	v_cmp_lt_f32_e64 s[14:15], |v0|, s59
	s_nop 1
	v_cndmask_b32_e64 v0, v0, v159, s[14:15]
	v_cndmask_b32_e32 v159, 0, v223, vcc
	v_sub_f32_e32 v0, v0, v159
	v_add_f32_e32 v0, v158, v0
	v_mul_f32_e32 v0, 0xbfb8aa3b, v0
	global_store_dword v[178:179], v0, off offset:4
	v_mov_b32_e32 v0, v229
	v_fmac_f32_e32 v0, v49, v194
	v_max_f32_e64 v158, -v0, 0
	v_mul_f32_e64 v0, |v0|, s51
	v_exp_f32_e32 v0, v0
	s_mov_b32 s51, 0x3f317217
	v_add_f32_e32 v0, 1.0, v0
	v_cmp_gt_f32_e32 vcc, s77, v0
	s_nop 1
	v_cndmask_b32_e64 v159, 0, 32, vcc
	v_ldexp_f32 v0, v0, v159
	v_log_f32_e32 v0, v0
	s_nop 0
	v_mul_f32_e32 v159, 0x3f317217, v0
	v_fma_f32 v159, v0, s58, -v159
	v_fmac_f32_e32 v159, 0x3377d1cf, v0
	v_fmac_f32_e32 v159, 0x3f317217, v0
	v_cmp_lt_f32_e64 s[14:15], |v0|, s59
	s_nop 1
	v_cndmask_b32_e64 v0, v0, v159, s[14:15]
	v_cndmask_b32_e32 v159, 0, v223, vcc
	v_sub_f32_e32 v0, v0, v159
	v_add_f32_e32 v0, v158, v0
	v_mul_f32_e32 v0, 0xbfb8aa3b, v0
	global_store_dword v[180:181], v0, off offset:4
	s_and_saveexec_b64 s[14:15], s[4:5]
	s_cbranch_execz .LBB0_284
	v_mov_b32_e32 v0, v230
	v_lshl_add_u64 v[200:201], v[130:131], 0, v[132:133]
	v_fmac_f32_e32 v0, v42, v194
	v_mul_f32_e64 v158, |v0|, s55
	v_exp_f32_e32 v158, v158
	v_max_f32_e64 v0, -v0, 0
	v_add_f32_e32 v158, 1.0, v158
	v_cmp_gt_f32_e32 vcc, s77, v158
	s_nop 1
	v_cndmask_b32_e64 v159, 0, 32, vcc
	v_ldexp_f32 v158, v158, v159
	v_log_f32_e32 v158, v158
	v_cndmask_b32_e32 v159, 0, v223, vcc
	v_mul_f32_e32 v162, 0x3f317217, v158
	v_fma_f32 v162, v158, s51, -v162
	v_fmac_f32_e32 v162, 0x3377d1cf, v158
	v_fmac_f32_e32 v162, 0x3f317217, v158
	v_cmp_lt_f32_e64 vcc, |v158|, s78
	s_nop 1
	v_cndmask_b32_e32 v158, v158, v162, vcc
	v_sub_f32_e32 v158, v158, v159
	v_add_f32_e32 v0, v0, v158
	v_mul_f32_e32 v0, 0xbfb8aa3b, v0
	global_store_dword v[200:201], v0, off offset:4
	s_or_b64 exec, exec, s[14:15]
	s_and_saveexec_b64 s[14:15], s[6:7]
	s_cbranch_execnz .LBB0_285

.LBB0_283:
	v_mov_b32_e32 v0, v232
	v_lshl_add_u64 v[200:201], v[130:131], 0, v[136:137]
	v_fmac_f32_e32 v0, v44, v194
	v_mul_f32_e64 v158, |v0|, s55
	v_exp_f32_e32 v158, v158
	v_max_f32_e64 v0, -v0, 0
	v_add_f32_e32 v158, 1.0, v158
	v_cmp_gt_f32_e32 vcc, s77, v158
	s_nop 1
	v_cndmask_b32_e64 v159, 0, 32, vcc
	v_ldexp_f32 v158, v158, v159
	v_log_f32_e32 v158, v158
	v_cndmask_b32_e32 v159, 0, v223, vcc
	v_mul_f32_e32 v162, 0x3f317217, v158
	v_fma_f32 v162, v158, s51, -v162
	v_fmac_f32_e32 v162, 0x3377d1cf, v158
	v_fmac_f32_e32 v162, 0x3f317217, v158
	v_cmp_lt_f32_e64 vcc, |v158|, s78
	s_nop 1
	v_cndmask_b32_e32 v158, v158, v162, vcc
	v_sub_f32_e32 v158, v158, v159
	v_add_f32_e32 v0, v0, v158
	v_mul_f32_e32 v0, 0xbfb8aa3b, v0
	global_store_dword v[200:201], v0, off offset:4
	s_or_b64 exec, exec, s[14:15]
	s_and_saveexec_b64 s[14:15], s[10:11]
	s_cbranch_execnz .LBB0_287
	s_branch .LBB0_288

.LBB0_285:
	v_mov_b32_e32 v0, v231
	v_lshl_add_u64 v[200:201], v[130:131], 0, v[134:135]
	v_fmac_f32_e32 v0, v43, v194
	v_mul_f32_e64 v158, |v0|, s55
	v_exp_f32_e32 v158, v158
	v_max_f32_e64 v0, -v0, 0
	v_add_f32_e32 v158, 1.0, v158
	v_cmp_gt_f32_e32 vcc, s77, v158
	s_nop 1
	v_cndmask_b32_e64 v159, 0, 32, vcc
	v_ldexp_f32 v158, v158, v159
	v_log_f32_e32 v158, v158
	v_cndmask_b32_e32 v159, 0, v223, vcc
	v_mul_f32_e32 v162, 0x3f317217, v158
	v_fma_f32 v162, v158, s51, -v162
	v_fmac_f32_e32 v162, 0x3377d1cf, v158
	v_fmac_f32_e32 v162, 0x3f317217, v158
	v_cmp_lt_f32_e64 vcc, |v158|, s78
	s_nop 1
	v_cndmask_b32_e32 v158, v158, v162, vcc
	v_sub_f32_e32 v158, v158, v159
	v_add_f32_e32 v0, v0, v158
	v_mul_f32_e32 v0, 0xbfb8aa3b, v0
	global_store_dword v[200:201], v0, off offset:4
	s_or_b64 exec, exec, s[14:15]
	s_and_saveexec_b64 s[14:15], s[8:9]
	s_cbranch_execnz .LBB0_283

.LBB0_287:
	v_mov_b32_e32 v0, v233
	v_lshl_add_u64 v[200:201], v[130:131], 0, v[176:177]
	v_fmac_f32_e32 v0, v45, v194
	v_mul_f32_e64 v158, |v0|, s55
	v_exp_f32_e32 v158, v158
	v_max_f32_e64 v0, -v0, 0
	v_add_f32_e32 v158, 1.0, v158
	v_cmp_gt_f32_e32 vcc, s77, v158
	s_nop 1
	v_cndmask_b32_e64 v159, 0, 32, vcc
	v_ldexp_f32 v158, v158, v159
	v_log_f32_e32 v158, v158
	v_cndmask_b32_e32 v159, 0, v223, vcc
	v_mul_f32_e32 v162, 0x3f317217, v158
	v_fma_f32 v162, v158, s51, -v162
	v_fmac_f32_e32 v162, 0x3377d1cf, v158
	v_fmac_f32_e32 v162, 0x3f317217, v158
	v_cmp_lt_f32_e64 vcc, |v158|, s78
	s_nop 1
	v_cndmask_b32_e32 v158, v158, v162, vcc
	v_sub_f32_e32 v158, v158, v159
	v_add_f32_e32 v0, v0, v158
	v_mul_f32_e32 v0, 0xbfb8aa3b, v0
	global_store_dword v[200:201], v0, off offset:4
.LBB0_288:
	s_or_b64 exec, exec, s[14:15]
	v_mov_b32_e32 v0, v226
	s_mov_b32 s51, 0xbfb8aa3b
	v_fmac_f32_e32 v0, v30, v193
	v_max_f32_e64 v158, -v0, 0
	v_mul_f32_e64 v0, |v0|, s51
	v_exp_f32_e32 v0, v0
	s_nop 0
	v_add_f32_e32 v0, 1.0, v0
	v_cmp_gt_f32_e32 vcc, s77, v0
	s_nop 1
	v_cndmask_b32_e64 v159, 0, 32, vcc
	v_ldexp_f32 v0, v0, v159
	v_log_f32_e32 v0, v0
	s_nop 0
	v_mul_f32_e32 v159, 0x3f317217, v0
	v_fma_f32 v159, v0, s58, -v159
	v_fmac_f32_e32 v159, 0x3377d1cf, v0
	v_fmac_f32_e32 v159, 0x3f317217, v0
	v_cmp_lt_f32_e64 s[14:15], |v0|, s59
	s_nop 1
	v_cndmask_b32_e64 v0, v0, v159, s[14:15]
	v_cndmask_b32_e32 v159, 0, v223, vcc
	v_sub_f32_e32 v0, v0, v159
	v_add_f32_e32 v0, v158, v0
	v_mul_f32_e32 v0, 0xbfb8aa3b, v0
	global_store_dword v[184:185], v0, off offset:8
	v_mov_b32_e32 v0, v227
	v_fmac_f32_e32 v0, v31, v193
	v_max_f32_e64 v158, -v0, 0
	v_mul_f32_e64 v0, |v0|, s51
	v_exp_f32_e32 v0, v0
	s_nop 0
	v_add_f32_e32 v0, 1.0, v0
	v_cmp_gt_f32_e32 vcc, s77, v0
	s_nop 1
	v_cndmask_b32_e64 v159, 0, 32, vcc
	v_ldexp_f32 v0, v0, v159
	v_log_f32_e32 v0, v0
	s_nop 0
	v_mul_f32_e32 v159, 0x3f317217, v0
	v_fma_f32 v159, v0, s58, -v159
	v_fmac_f32_e32 v159, 0x3377d1cf, v0
	v_fmac_f32_e32 v159, 0x3f317217, v0
	v_cmp_lt_f32_e64 s[14:15], |v0|, s59
	s_nop 1
	v_cndmask_b32_e64 v0, v0, v159, s[14:15]
	v_cndmask_b32_e32 v159, 0, v223, vcc
	v_sub_f32_e32 v0, v0, v159
	v_add_f32_e32 v0, v158, v0
	v_mul_f32_e32 v0, 0xbfb8aa3b, v0
	global_store_dword v[182:183], v0, off offset:8
	v_mov_b32_e32 v0, v228
	v_fmac_f32_e32 v0, v32, v193
	v_max_f32_e64 v158, -v0, 0
	v_mul_f32_e64 v0, |v0|, s51
	v_exp_f32_e32 v0, v0
	s_nop 0
	v_add_f32_e32 v0, 1.0, v0
	v_cmp_gt_f32_e32 vcc, s77, v0
	s_nop 1
	v_cndmask_b32_e64 v159, 0, 32, vcc
	v_ldexp_f32 v0, v0, v159
	v_log_f32_e32 v0, v0
	s_nop 0
	v_mul_f32_e32 v159, 0x3f317217, v0
	v_fma_f32 v159, v0, s58, -v159
	v_fmac_f32_e32 v159, 0x3377d1cf, v0
	v_fmac_f32_e32 v159, 0x3f317217, v0
	v_cmp_lt_f32_e64 s[14:15], |v0|, s59
	s_nop 1
	v_cndmask_b32_e64 v0, v0, v159, s[14:15]
	v_cndmask_b32_e32 v159, 0, v223, vcc
	v_sub_f32_e32 v0, v0, v159
	v_add_f32_e32 v0, v158, v0
	v_mul_f32_e32 v0, 0xbfb8aa3b, v0
	global_store_dword v[178:179], v0, off offset:8
	v_mov_b32_e32 v0, v229
	v_fmac_f32_e32 v0, v33, v193
	v_max_f32_e64 v158, -v0, 0
	v_mul_f32_e64 v0, |v0|, s51
	v_exp_f32_e32 v0, v0
	s_mov_b32 s51, 0x3f317217
	v_add_f32_e32 v0, 1.0, v0
	v_cmp_gt_f32_e32 vcc, s77, v0
	s_nop 1
	v_cndmask_b32_e64 v159, 0, 32, vcc
	v_ldexp_f32 v0, v0, v159
	v_log_f32_e32 v0, v0
	s_nop 0
	v_mul_f32_e32 v159, 0x3f317217, v0
	v_fma_f32 v159, v0, s58, -v159
	v_fmac_f32_e32 v159, 0x3377d1cf, v0
	v_fmac_f32_e32 v159, 0x3f317217, v0
	v_cmp_lt_f32_e64 s[14:15], |v0|, s59
	s_nop 1
	v_cndmask_b32_e64 v0, v0, v159, s[14:15]
	v_cndmask_b32_e32 v159, 0, v223, vcc
	v_sub_f32_e32 v0, v0, v159
	v_add_f32_e32 v0, v158, v0
	v_mul_f32_e32 v0, 0xbfb8aa3b, v0
	global_store_dword v[180:181], v0, off offset:8
	s_and_saveexec_b64 s[14:15], s[4:5]
	s_cbranch_execz .LBB0_292
	v_mov_b32_e32 v0, v230
	v_lshl_add_u64 v[200:201], v[130:131], 0, v[132:133]
	v_fmac_f32_e32 v0, v26, v193
	v_mul_f32_e64 v158, |v0|, s55
	v_exp_f32_e32 v158, v158
	v_max_f32_e64 v0, -v0, 0
	v_add_f32_e32 v158, 1.0, v158
	v_cmp_gt_f32_e32 vcc, s77, v158
	s_nop 1
	v_cndmask_b32_e64 v159, 0, 32, vcc
	v_ldexp_f32 v158, v158, v159
	v_log_f32_e32 v158, v158
	v_cndmask_b32_e32 v159, 0, v223, vcc
	v_mul_f32_e32 v162, 0x3f317217, v158
	v_fma_f32 v162, v158, s51, -v162
	v_fmac_f32_e32 v162, 0x3377d1cf, v158
	v_fmac_f32_e32 v162, 0x3f317217, v158
	v_cmp_lt_f32_e64 vcc, |v158|, s78
	s_nop 1
	v_cndmask_b32_e32 v158, v158, v162, vcc
	v_sub_f32_e32 v158, v158, v159
	v_add_f32_e32 v0, v0, v158
	v_mul_f32_e32 v0, 0xbfb8aa3b, v0
	global_store_dword v[200:201], v0, off offset:8
	s_or_b64 exec, exec, s[14:15]
	s_and_saveexec_b64 s[14:15], s[6:7]
	s_cbranch_execnz .LBB0_293

.LBB0_291:
	v_mov_b32_e32 v0, v232
	v_lshl_add_u64 v[200:201], v[130:131], 0, v[136:137]
	v_fmac_f32_e32 v0, v28, v193
	v_mul_f32_e64 v158, |v0|, s55
	v_exp_f32_e32 v158, v158
	v_max_f32_e64 v0, -v0, 0
	v_add_f32_e32 v158, 1.0, v158
	v_cmp_gt_f32_e32 vcc, s77, v158
	s_nop 1
	v_cndmask_b32_e64 v159, 0, 32, vcc
	v_ldexp_f32 v158, v158, v159
	v_log_f32_e32 v158, v158
	v_cndmask_b32_e32 v159, 0, v223, vcc
	v_mul_f32_e32 v162, 0x3f317217, v158
	v_fma_f32 v162, v158, s51, -v162
	v_fmac_f32_e32 v162, 0x3377d1cf, v158
	v_fmac_f32_e32 v162, 0x3f317217, v158
	v_cmp_lt_f32_e64 vcc, |v158|, s78
	s_nop 1
	v_cndmask_b32_e32 v158, v158, v162, vcc
	v_sub_f32_e32 v158, v158, v159
	v_add_f32_e32 v0, v0, v158
	v_mul_f32_e32 v0, 0xbfb8aa3b, v0
	global_store_dword v[200:201], v0, off offset:8
	s_or_b64 exec, exec, s[14:15]
	s_and_saveexec_b64 s[14:15], s[10:11]
	s_cbranch_execnz .LBB0_295
	s_branch .LBB0_296

.LBB0_293:
	v_mov_b32_e32 v0, v231
	v_lshl_add_u64 v[200:201], v[130:131], 0, v[134:135]
	v_fmac_f32_e32 v0, v27, v193
	v_mul_f32_e64 v158, |v0|, s55
	v_exp_f32_e32 v158, v158
	v_max_f32_e64 v0, -v0, 0
	v_add_f32_e32 v158, 1.0, v158
	v_cmp_gt_f32_e32 vcc, s77, v158
	s_nop 1
	v_cndmask_b32_e64 v159, 0, 32, vcc
	v_ldexp_f32 v158, v158, v159
	v_log_f32_e32 v158, v158
	v_cndmask_b32_e32 v159, 0, v223, vcc
	v_mul_f32_e32 v162, 0x3f317217, v158
	v_fma_f32 v162, v158, s51, -v162
	v_fmac_f32_e32 v162, 0x3377d1cf, v158
	v_fmac_f32_e32 v162, 0x3f317217, v158
	v_cmp_lt_f32_e64 vcc, |v158|, s78
	s_nop 1
	v_cndmask_b32_e32 v158, v158, v162, vcc
	v_sub_f32_e32 v158, v158, v159
	v_add_f32_e32 v0, v0, v158
	v_mul_f32_e32 v0, 0xbfb8aa3b, v0
	global_store_dword v[200:201], v0, off offset:8
	s_or_b64 exec, exec, s[14:15]
	s_and_saveexec_b64 s[14:15], s[8:9]
	s_cbranch_execnz .LBB0_291

.LBB0_295:
	v_mov_b32_e32 v0, v233
	v_lshl_add_u64 v[200:201], v[130:131], 0, v[176:177]
	v_fmac_f32_e32 v0, v29, v193
	v_mul_f32_e64 v158, |v0|, s55
	v_exp_f32_e32 v158, v158
	v_max_f32_e64 v0, -v0, 0
	v_add_f32_e32 v158, 1.0, v158
	v_cmp_gt_f32_e32 vcc, s77, v158
	s_nop 1
	v_cndmask_b32_e64 v159, 0, 32, vcc
	v_ldexp_f32 v158, v158, v159
	v_log_f32_e32 v158, v158
	v_cndmask_b32_e32 v159, 0, v223, vcc
	v_mul_f32_e32 v162, 0x3f317217, v158
	v_fma_f32 v162, v158, s51, -v162
	v_fmac_f32_e32 v162, 0x3377d1cf, v158
	v_fmac_f32_e32 v162, 0x3f317217, v158
	v_cmp_lt_f32_e64 vcc, |v158|, s78
	s_nop 1
	v_cndmask_b32_e32 v158, v158, v162, vcc
	v_sub_f32_e32 v158, v158, v159
	v_add_f32_e32 v0, v0, v158
	v_mul_f32_e32 v0, 0xbfb8aa3b, v0
	global_store_dword v[200:201], v0, off offset:8
.LBB0_296:
	s_or_b64 exec, exec, s[14:15]
	v_mov_b32_e32 v0, v226
	s_mov_b32 s51, 0xbfb8aa3b
	v_fmac_f32_e32 v0, v14, v191
	v_max_f32_e64 v158, -v0, 0
	v_mul_f32_e64 v0, |v0|, s51
	v_exp_f32_e32 v0, v0
	s_nop 0
	v_add_f32_e32 v0, 1.0, v0
	v_cmp_gt_f32_e32 vcc, s77, v0
	s_nop 1
	v_cndmask_b32_e64 v159, 0, 32, vcc
	v_ldexp_f32 v0, v0, v159
	v_log_f32_e32 v0, v0
	s_nop 0
	v_mul_f32_e32 v159, 0x3f317217, v0
	v_fma_f32 v159, v0, s58, -v159
	v_fmac_f32_e32 v159, 0x3377d1cf, v0
	v_fmac_f32_e32 v159, 0x3f317217, v0
	v_cmp_lt_f32_e64 s[14:15], |v0|, s59
	s_nop 1
	v_cndmask_b32_e64 v0, v0, v159, s[14:15]
	v_cndmask_b32_e32 v159, 0, v223, vcc
	v_sub_f32_e32 v0, v0, v159
	v_add_f32_e32 v0, v158, v0
	v_mul_f32_e32 v0, 0xbfb8aa3b, v0
	global_store_dword v[184:185], v0, off offset:12
	v_mov_b32_e32 v0, v227
	v_fmac_f32_e32 v0, v15, v191
	v_max_f32_e64 v158, -v0, 0
	v_mul_f32_e64 v0, |v0|, s51
	v_exp_f32_e32 v0, v0
	s_nop 0
	v_add_f32_e32 v0, 1.0, v0
	v_cmp_gt_f32_e32 vcc, s77, v0
	s_nop 1
	v_cndmask_b32_e64 v159, 0, 32, vcc
	v_ldexp_f32 v0, v0, v159
	v_log_f32_e32 v0, v0
	s_nop 0
	v_mul_f32_e32 v159, 0x3f317217, v0
	v_fma_f32 v159, v0, s58, -v159
	v_fmac_f32_e32 v159, 0x3377d1cf, v0
	v_fmac_f32_e32 v159, 0x3f317217, v0
	v_cmp_lt_f32_e64 s[14:15], |v0|, s59
	s_nop 1
	v_cndmask_b32_e64 v0, v0, v159, s[14:15]
	v_cndmask_b32_e32 v159, 0, v223, vcc
	v_sub_f32_e32 v0, v0, v159
	v_add_f32_e32 v0, v158, v0
	v_mul_f32_e32 v0, 0xbfb8aa3b, v0
	global_store_dword v[182:183], v0, off offset:12
	v_mov_b32_e32 v0, v228
	v_fmac_f32_e32 v0, v16, v191
	v_max_f32_e64 v158, -v0, 0
	v_mul_f32_e64 v0, |v0|, s51
	v_exp_f32_e32 v0, v0
	s_nop 0
	v_add_f32_e32 v0, 1.0, v0
	v_cmp_gt_f32_e32 vcc, s77, v0
	s_nop 1
	v_cndmask_b32_e64 v159, 0, 32, vcc
	v_ldexp_f32 v0, v0, v159
	v_log_f32_e32 v0, v0
	s_nop 0
	v_mul_f32_e32 v159, 0x3f317217, v0
	v_fma_f32 v159, v0, s58, -v159
	v_fmac_f32_e32 v159, 0x3377d1cf, v0
	v_fmac_f32_e32 v159, 0x3f317217, v0
	v_cmp_lt_f32_e64 s[14:15], |v0|, s59
	s_nop 1
	v_cndmask_b32_e64 v0, v0, v159, s[14:15]
	v_cndmask_b32_e32 v159, 0, v223, vcc
	v_sub_f32_e32 v0, v0, v159
	v_add_f32_e32 v0, v158, v0
	v_mul_f32_e32 v0, 0xbfb8aa3b, v0
	global_store_dword v[178:179], v0, off offset:12
	v_mov_b32_e32 v0, v229
	v_fmac_f32_e32 v0, v17, v191
	v_max_f32_e64 v158, -v0, 0
	v_mul_f32_e64 v0, |v0|, s51
	v_exp_f32_e32 v0, v0
	s_mov_b32 s51, 0x3f317217
	v_add_f32_e32 v0, 1.0, v0
	v_cmp_gt_f32_e32 vcc, s77, v0
	s_nop 1
	v_cndmask_b32_e64 v159, 0, 32, vcc
	v_ldexp_f32 v0, v0, v159
	v_log_f32_e32 v0, v0
	s_nop 0
	v_mul_f32_e32 v159, 0x3f317217, v0
	v_fma_f32 v159, v0, s58, -v159
	v_fmac_f32_e32 v159, 0x3377d1cf, v0
	v_fmac_f32_e32 v159, 0x3f317217, v0
	v_cmp_lt_f32_e64 s[14:15], |v0|, s59
	s_nop 1
	v_cndmask_b32_e64 v0, v0, v159, s[14:15]
	v_cndmask_b32_e32 v159, 0, v223, vcc
	v_sub_f32_e32 v0, v0, v159
	v_add_f32_e32 v0, v158, v0
	v_mul_f32_e32 v0, 0xbfb8aa3b, v0
	global_store_dword v[180:181], v0, off offset:12
	s_and_saveexec_b64 s[14:15], s[4:5]
	s_cbranch_execz .LBB0_300
	v_mov_b32_e32 v0, v230
	v_lshl_add_u64 v[132:133], v[130:131], 0, v[132:133]
	v_fmac_f32_e32 v0, v10, v191
	v_mul_f32_e64 v158, |v0|, s55
	v_exp_f32_e32 v158, v158
	v_max_f32_e64 v0, -v0, 0
	v_add_f32_e32 v158, 1.0, v158
	v_cmp_gt_f32_e32 vcc, s77, v158
	s_nop 1
	v_cndmask_b32_e64 v159, 0, 32, vcc
	v_ldexp_f32 v158, v158, v159
	v_log_f32_e32 v158, v158
	v_cndmask_b32_e32 v159, 0, v223, vcc
	v_mul_f32_e32 v162, 0x3f317217, v158
	v_fma_f32 v162, v158, s51, -v162
	v_fmac_f32_e32 v162, 0x3377d1cf, v158
	v_fmac_f32_e32 v162, 0x3f317217, v158
	v_cmp_lt_f32_e64 vcc, |v158|, s78
	s_nop 1
	v_cndmask_b32_e32 v158, v158, v162, vcc
	v_sub_f32_e32 v158, v158, v159
	v_add_f32_e32 v0, v0, v158
	v_mul_f32_e32 v0, 0xbfb8aa3b, v0
	global_store_dword v[132:133], v0, off offset:12
	s_or_b64 exec, exec, s[14:15]
	s_and_saveexec_b64 s[14:15], s[6:7]
	s_cbranch_execnz .LBB0_301

.LBB0_299:
	v_mov_b32_e32 v0, v232
	v_fmac_f32_e32 v0, v12, v191
	v_mul_f32_e64 v132, |v0|, s55
	v_exp_f32_e32 v132, v132
	v_max_f32_e64 v0, -v0, 0
	v_add_f32_e32 v132, 1.0, v132
	v_cmp_gt_f32_e32 vcc, s77, v132
	s_nop 1
	v_cndmask_b32_e64 v133, 0, 32, vcc
	v_ldexp_f32 v132, v132, v133
	v_log_f32_e32 v132, v132
	v_cndmask_b32_e32 v133, 0, v223, vcc
	v_mul_f32_e32 v134, 0x3f317217, v132
	v_fma_f32 v134, v132, s51, -v134
	v_fmac_f32_e32 v134, 0x3377d1cf, v132
	v_fmac_f32_e32 v134, 0x3f317217, v132
	v_cmp_lt_f32_e64 vcc, |v132|, s78
	s_nop 1
	v_cndmask_b32_e32 v132, v132, v134, vcc
	v_sub_f32_e32 v132, v132, v133
	v_add_f32_e32 v0, v0, v132
	v_mul_f32_e32 v0, 0xbfb8aa3b, v0
	v_lshl_add_u64 v[132:133], v[130:131], 0, v[136:137]
	global_store_dword v[132:133], v0, off offset:12
	s_or_b64 exec, exec, s[14:15]
	s_and_b64 exec, exec, s[10:11]
	s_cbranch_execnz .LBB0_303
	s_branch .LBB0_304

.LBB0_301:
	v_mov_b32_e32 v0, v231
	v_fmac_f32_e32 v0, v11, v191
	v_mul_f32_e64 v132, |v0|, s55
	v_exp_f32_e32 v132, v132
	v_max_f32_e64 v0, -v0, 0
	v_add_f32_e32 v132, 1.0, v132
	v_cmp_gt_f32_e32 vcc, s77, v132
	s_nop 1
	v_cndmask_b32_e64 v133, 0, 32, vcc
	v_ldexp_f32 v132, v132, v133
	v_log_f32_e32 v132, v132
	v_cndmask_b32_e32 v133, 0, v223, vcc
	v_mul_f32_e32 v158, 0x3f317217, v132
	v_fma_f32 v158, v132, s51, -v158
	v_fmac_f32_e32 v158, 0x3377d1cf, v132
	v_fmac_f32_e32 v158, 0x3f317217, v132
	v_cmp_lt_f32_e64 vcc, |v132|, s78
	s_nop 1
	v_cndmask_b32_e32 v132, v132, v158, vcc
	v_sub_f32_e32 v132, v132, v133
	v_add_f32_e32 v0, v0, v132
	v_mul_f32_e32 v0, 0xbfb8aa3b, v0
	v_lshl_add_u64 v[132:133], v[130:131], 0, v[134:135]
	global_store_dword v[132:133], v0, off offset:12
	s_or_b64 exec, exec, s[14:15]
	s_and_saveexec_b64 s[14:15], s[8:9]
	s_cbranch_execnz .LBB0_299

.LBB0_303:
	v_mov_b32_e32 v0, v233
	v_lshl_add_u64 v[130:131], v[130:131], 0, v[176:177]
	v_fmac_f32_e32 v0, v13, v191
	v_mul_f32_e64 v132, |v0|, s55
	v_exp_f32_e32 v132, v132
	v_max_f32_e64 v0, -v0, 0
	v_add_f32_e32 v132, 1.0, v132
	v_cmp_gt_f32_e32 vcc, s77, v132
	s_nop 1
	v_cndmask_b32_e64 v133, 0, 32, vcc
	v_ldexp_f32 v132, v132, v133
	v_log_f32_e32 v132, v132
	v_cndmask_b32_e32 v133, 0, v223, vcc
	v_mul_f32_e32 v134, 0x3f317217, v132
	v_fma_f32 v134, v132, s51, -v134
	v_fmac_f32_e32 v134, 0x3377d1cf, v132
	v_fmac_f32_e32 v134, 0x3f317217, v132
	v_cmp_lt_f32_e64 vcc, |v132|, s78
	s_nop 1
	v_cndmask_b32_e32 v132, v132, v134, vcc
	v_sub_f32_e32 v132, v132, v133
	v_add_f32_e32 v0, v0, v132
	v_mul_f32_e32 v0, 0xbfb8aa3b, v0
	global_store_dword v[130:131], v0, off offset:12
